# r-table builds (phases B and F) with line-coalesced statistics loads + DPP row reduction; two-slot bias LUT cache in diff attention
# speedup vs baseline: 1.0145x; 1.0025x over previous
.LBB0_84:
	s_lshl_b32 s10, s6, 20
	s_mov_b32 s11, s85
	s_lshl_b64 s[10:11], s[10:11], 2
	v_readlane_b32 s6, v252, 55
	s_add_u32 s10, s6, s10
	v_readlane_b32 s6, v252, 56
	s_addc_u32 s11, s6, s11
	s_lshl_b32 s28, s8, 3
	v_cvt_f32_ubyte0_e32 v0, s28
	v_rcp_iflag_f32_e32 v2, v0
	v_writelane_b32 v255, s10, 1
	s_sub_i32 s8, 0, s28
	v_mov_b32_e32 v0, v208
	v_mul_f32_e32 v2, 0x4f7ffffe, v2
	v_cvt_u32_f32_e32 v2, v2
	v_writelane_b32 v255, s11, 2
	s_movk_i32 s6, 0x100
	v_readfirstlane_b32 s10, v2
	s_mul_i32 s8, s8, s10
	s_mul_hi_u32 s8, s10, s8
	v_cmp_gt_i32_e64 s[42:43], s6, v0
	s_add_i32 s30, s10, s8
	s_ashr_i32 s10, s15, 31
	v_readlane_b32 s6, v254, 46
	s_mul_hi_u32 s12, s6, s15
	s_mul_i32 s10, s6, s10
	v_readlane_b32 s6, v254, 47
	s_sub_i32 s8, 0, s15
	s_add_i32 s10, s12, s10
	s_mul_i32 s12, s6, s15
	s_or_b32 s29, s28, 1
	s_sub_i32 s11, s8, s14
	s_add_i32 s10, s10, s12
	v_lshl_add_u32 v2, v0, 2, s90
	v_lshlrev_b32_e32 v42, 4, v0
	v_add_u32_e32 v43, 0x1000, v42
	v_add_u32_e32 v44, 0x2000, v42
	v_add_u32_e32 v45, 0x3000, v42
	v_add_u32_e32 v46, 0x4000, v42
	v_add_u32_e32 v47, 0x5000, v42
	v_add_u32_e32 v48, 0x6000, v42
	v_add_u32_e32 v49, 0x7000, v42
	v_and_b32_e32 v50, 1, v0
	v_and_b32_e32 v51, 2, v0
	v_and_b32_e32 v52, 4, v0
	v_and_b32_e32 v53, 7, v0
	v_lshrrev_b32_e32 v54, 3, v0
	v_lshl_add_u32 v53, v53, 5, v54
	v_lshl_add_u32 v53, v53, 2, s90
	s_mov_b64 s[50:51], s[2:3]
	s_branch .LBB0_87
.LBB0_85:
	s_or_b64 exec, exec, s[52:53]
	s_add_i32 s9, s9, 1
	s_add_u32 s50, s50, s98
	s_addc_u32 s51, s51, s75
	s_cmp_eq_u32 s9, 14
	v_add_u32_e32 v2, 0x400, v2
	v_add_u32_e32 v53, 0x400, v53
	s_cselect_b64 s[52:53], -1, 0

.LBB0_111:
	s_andn2_b64 vcc, exec, s[54:55]
	s_mov_b64 s[52:53], -1
	s_cbranch_vccnz .LBB0_86
	s_and_saveexec_b64 s[52:53], s[42:43]
	s_cbranch_execz .LBB0_85
	v_readlane_b32 s6, v255, 1
	v_readlane_b32 s7, v255, 2
	s_lshl_b32 s100, s22, 15
	s_add_u32 s100, s6, s100
	s_addc_u32 s101, s7, 0
	s_nop 1
	global_load_dwordx4 v[4:7], v42, s[100:101]
	global_load_dwordx4 v[8:11], v43, s[100:101]
	global_load_dwordx4 v[12:15], v44, s[100:101]
	global_load_dwordx4 v[16:19], v45, s[100:101]
	global_load_dwordx4 v[26:29], v46, s[100:101]
	global_load_dwordx4 v[30:33], v47, s[100:101]
	global_load_dwordx4 v[34:37], v48, s[100:101]
	global_load_dwordx4 v[38:41], v49, s[100:101]
	s_waitcnt vmcnt(0)
	v_add_f32_e32 v4, v4, v5
	v_add_f32_e32 v8, v8, v9
	v_add_f32_e32 v12, v12, v13
	v_add_f32_e32 v16, v16, v17
	v_add_f32_e32 v26, v26, v27
	v_add_f32_e32 v30, v30, v31
	v_add_f32_e32 v34, v34, v35
	v_add_f32_e32 v38, v38, v39
	v_add_f32_e32 v6, v6, v7
	v_add_f32_e32 v10, v10, v11
	v_add_f32_e32 v14, v14, v15
	v_add_f32_e32 v18, v18, v19
	v_add_f32_e32 v28, v28, v29
	v_add_f32_e32 v32, v32, v33
	v_add_f32_e32 v36, v36, v37
	v_add_f32_e32 v40, v40, v41
	v_add_f32_e32 v4, v4, v6
	v_add_f32_e32 v8, v8, v10
	v_add_f32_e32 v12, v12, v14
	v_add_f32_e32 v16, v16, v18
	v_add_f32_e32 v26, v26, v28
	v_add_f32_e32 v30, v30, v32
	v_add_f32_e32 v34, v34, v36
	v_add_f32_e32 v38, v38, v40
	v_add_f32_dpp v4, v4, v4 quad_perm:[1,0,3,2] row_mask:0xf bank_mask:0xf
	v_add_f32_dpp v8, v8, v8 quad_perm:[1,0,3,2] row_mask:0xf bank_mask:0xf
	v_add_f32_dpp v12, v12, v12 quad_perm:[1,0,3,2] row_mask:0xf bank_mask:0xf
	v_add_f32_dpp v16, v16, v16 quad_perm:[1,0,3,2] row_mask:0xf bank_mask:0xf
	v_add_f32_dpp v26, v26, v26 quad_perm:[1,0,3,2] row_mask:0xf bank_mask:0xf
	v_add_f32_dpp v30, v30, v30 quad_perm:[1,0,3,2] row_mask:0xf bank_mask:0xf
	v_add_f32_dpp v34, v34, v34 quad_perm:[1,0,3,2] row_mask:0xf bank_mask:0xf
	v_add_f32_dpp v38, v38, v38 quad_perm:[1,0,3,2] row_mask:0xf bank_mask:0xf
	v_add_f32_dpp v4, v4, v4 quad_perm:[2,3,0,1] row_mask:0xf bank_mask:0xf
	v_add_f32_dpp v8, v8, v8 quad_perm:[2,3,0,1] row_mask:0xf bank_mask:0xf
	v_add_f32_dpp v12, v12, v12 quad_perm:[2,3,0,1] row_mask:0xf bank_mask:0xf
	v_add_f32_dpp v16, v16, v16 quad_perm:[2,3,0,1] row_mask:0xf bank_mask:0xf
	v_add_f32_dpp v26, v26, v26 quad_perm:[2,3,0,1] row_mask:0xf bank_mask:0xf
	v_add_f32_dpp v30, v30, v30 quad_perm:[2,3,0,1] row_mask:0xf bank_mask:0xf
	v_add_f32_dpp v34, v34, v34 quad_perm:[2,3,0,1] row_mask:0xf bank_mask:0xf
	v_add_f32_dpp v38, v38, v38 quad_perm:[2,3,0,1] row_mask:0xf bank_mask:0xf
	v_add_f32_dpp v4, v4, v4 row_half_mirror row_mask:0xf bank_mask:0xf
	v_add_f32_dpp v8, v8, v8 row_half_mirror row_mask:0xf bank_mask:0xf
	v_add_f32_dpp v12, v12, v12 row_half_mirror row_mask:0xf bank_mask:0xf
	v_add_f32_dpp v16, v16, v16 row_half_mirror row_mask:0xf bank_mask:0xf
	v_add_f32_dpp v26, v26, v26 row_half_mirror row_mask:0xf bank_mask:0xf
	v_add_f32_dpp v30, v30, v30 row_half_mirror row_mask:0xf bank_mask:0xf
	v_add_f32_dpp v34, v34, v34 row_half_mirror row_mask:0xf bank_mask:0xf
	v_add_f32_dpp v38, v38, v38 row_half_mirror row_mask:0xf bank_mask:0xf
	v_cmp_ne_u32_e32 vcc, 0, v50
	s_nop 1
	v_cndmask_b32_e32 v4, v4, v8, vcc
	v_cndmask_b32_e32 v12, v12, v16, vcc
	v_cndmask_b32_e32 v26, v26, v30, vcc
	v_cndmask_b32_e32 v34, v34, v38, vcc
	v_cmp_ne_u32_e32 vcc, 0, v51
	s_nop 1
	v_cndmask_b32_e32 v4, v4, v12, vcc
	v_cndmask_b32_e32 v26, v26, v34, vcc
	v_cmp_ne_u32_e32 vcc, 0, v52
	s_nop 1
	v_cndmask_b32_e32 v3, v4, v26, vcc
	v_mov_b32_e32 v4, 0x3727c5ac
	v_fmamk_f32 v3, v3, 0x3a000000, v4
	v_rsq_f32_e32 v3, v3
	ds_write_b32 v53, v3
	s_branch .LBB0_85

.LBB0_245:
	s_or_b64 exec, exec, s[0:1]
	s_mov_b32 s47, -1
	s_mov_b32 s101, -1
	s_mov_b32 s46, 0
	s_branch .LBB0_252

.LBB0_252:
	s_bitcmp0_b32 s46, 0
	v_readlane_b32 s1, v252, 61
	s_mul_i32 s0, s46, s98
	s_cselect_b32 s1, s2, s1
	s_add_i32 s0, s1, s0
	s_cmpk_gt_i32 s0, 0x7ff
	s_cselect_b64 s[42:43], -1, 0
	s_and_b64 vcc, exec, s[42:43]
	s_cbranch_vccnz .LBB0_251
	s_ashr_i32 s1, s0, 31
	s_lshr_b32 s1, s1, 27
	s_add_i32 s8, s0, s1
	s_and_b32 s1, s8, 0xffffffe0
	s_sub_i32 s9, s0, s1
	s_and_b32 s10, s9, 15
	s_and_b32 s100, s46, 1
	s_lshl_b32 s100, s100, 11
	s_add_i32 s100, s100, s90
	s_bitcmp1_b32 s46, 0
	s_cselect_b32 vcc_lo, s101, s47
	s_cmp_eq_u32 s10, vcc_lo
	s_cbranch_scc1 .LBB0_261
	v_mov_b32_e32 v0, v208
	s_movk_i32 s0, 0x81
	s_nop 0
	v_cmp_gt_i32_e32 vcc, s0, v0
	s_and_saveexec_b64 s[0:1], vcc
	s_cbranch_execz .LBB0_260
	v_add_u32_e32 v3, -1, v0
	v_cmp_lt_i32_e32 vcc, 16, v0
	s_and_saveexec_b64 s[12:13], vcc
	s_xor_b64 s[40:41], exec, s[12:13]
	s_cbranch_execz .LBB0_257
	v_cvt_f32_u32_e32 v2, v3
	s_mov_b32 s6, 0x800000
	v_mul_f32_e32 v2, 0x3d800000, v2
	v_cmp_gt_f32_e32 vcc, s6, v2
	s_mov_b32 s6, 0x3f317217
	s_nop 0
	v_cndmask_b32_e64 v3, 0, 32, vcc
	v_ldexp_f32 v2, v2, v3
	v_log_f32_e32 v2, v2
	v_mov_b32_e32 v3, 0x41b17218
	v_cndmask_b32_e32 v3, 0, v3, vcc
	v_mul_f32_e32 v4, 0x3f317217, v2
	v_fma_f32 v4, v2, s6, -v4
	v_fmac_f32_e32 v4, 0x3377d1cf, v2
	s_mov_b32 s6, 0x7f800000
	v_fmac_f32_e32 v4, 0x3f317217, v2
	v_cmp_lt_f32_e64 vcc, |v2|, s6
	s_mov_b32 s6, 0x40051592
	s_nop 0
	v_cndmask_b32_e32 v2, v2, v4, vcc
	v_sub_f32_e32 v2, v2, v3
	v_div_scale_f32 v3, s[12:13], s6, s6, v2
	v_rcp_f32_e32 v4, v3
	v_div_scale_f32 v5, vcc, v2, s6, v2
	v_fma_f32 v6, -v3, v4, 1.0
	v_fmac_f32_e32 v4, v6, v4
	v_mul_f32_e32 v6, v5, v4
	v_fma_f32 v7, -v3, v6, v5
	v_fmac_f32_e32 v6, v7, v4
	v_fma_f32 v3, -v3, v6, v5
	v_div_fmas_f32 v3, v3, v4, v6
	v_div_fixup_f32 v2, v3, s6, v2
	v_mul_f32_e32 v2, 0x41800000, v2
	v_cvt_i32_f32_e32 v2, v2
	v_min_i32_e32 v2, 15, v2
	v_add_u32_e32 v2, 16, v2
.LBB0_257:
	s_andn2_saveexec_b64 s[40:41], s[40:41]
	v_max_i32_e32 v2, 0, v3
	s_or_b64 exec, exec, s[40:41]
	v_lshl_or_b32 v2, v2, 4, s10
	v_readlane_b32 s52, v252, 34
	v_ashrrev_i32_e32 v3, 31, v2
	v_readlane_b32 s54, v252, 36
	v_readlane_b32 s55, v252, 37
	s_lshl_b32 s6, s10, 2
	v_mov_b32_e32 v4, s6
	v_lshl_add_u64 v[2:3], v[2:3], 2, s[54:55]
	global_load_dword v2, v[2:3], off
	s_nop 0
	global_load_dword v3, v4, s[54:55] offset:1984
	v_lshl_add_u32 v4, v0, 2, 0
	v_cmp_lt_i32_e32 vcc, 0, v0
	v_readlane_b32 s53, v252, 35
	v_readlane_b32 s56, v252, 38
	v_readlane_b32 s57, v252, 39
	v_readlane_b32 s58, v252, 40
	v_readlane_b32 s59, v252, 41
	v_readlane_b32 s60, v252, 42
	v_readlane_b32 s61, v252, 43
	v_readlane_b32 s62, v252, 44
	v_readlane_b32 s63, v252, 45
	v_readlane_b32 s64, v252, 46
	v_readlane_b32 s65, v252, 47
	v_readlane_b32 s66, v252, 48
	v_readlane_b32 s67, v252, 49
	s_waitcnt vmcnt(0)
	v_sub_f32_e32 v2, v2, v3
	v_mul_f32_e32 v2, 0x3fb8aa3b, v2
	v_cndmask_b32_e32 v0, v211, v2, vcc
	v_add_u32_e32 v2, s100, v4
	ds_write_b32 v2, v0
.LBB0_260:
	s_or_b64 exec, exec, s[0:1]
	s_bitcmp1_b32 s46, 0
	s_cselect_b32 s101, s10, s101
	s_cselect_b32 s47, s47, s10
	s_waitcnt lgkmcnt(0)
	s_barrier

.LBB0_263:
	s_min_u32 s0, s30, 1
	s_lshl_b32 s0, s0, 15
	s_sub_i32 s6, s23, s0
	s_add_i32 s31, s9, -3
	s_add_i32 s0, s9, -1
	s_cmp_lt_u32 s31, s18
	s_cselect_b32 s84, s0, s27
	s_lshl_b64 s[0:1], s[84:85], 18
	v_lshl_add_u64 v[130:131], v[204:205], 0, s[0:1]
	v_lshl_add_u64 v[134:135], v[206:207], 0, s[0:1]
	s_add_i32 s0, s29, 0xffff8000
	s_and_b32 s0, s0, 0x10000
	s_add_i32 s0, s19, s0
	s_mov_b32 m0, s0
	s_waitcnt vmcnt(4)
	s_barrier
	global_load_lds_dwordx4 v[130:131], off
	v_lshl_add_u64 v[130:131], v[130:131], 0, s[72:73]
	s_add_i32 m0, s0, 0x2000
	s_nop 0
	global_load_lds_dwordx4 v[130:131], off
	s_add_i32 m0, s0, 0x4000
	v_lshl_add_u64 v[130:131], v[134:135], 0, s[96:97]
	global_load_lds_dwordx4 v[134:135], off
	s_add_i32 m0, s0, 0x6000
	s_add_i32 s0, s29, 0xfffe8000
	global_load_lds_dwordx4 v[130:131], off
	s_and_b32 s0, s0, 0x10000
	s_add_i32 s10, s0, 0
	v_add_u32_e32 v0, s10, v217
	v_add_u32_e32 v130, v0, v218
	v_add_u32_e32 v131, v0, v223
	v_add_u32_e32 v134, v0, v224
	v_add_u32_e32 v0, v0, v225
	ds_read_b128 v[178:181], v130
	ds_read_b128 v[182:185], v130 offset:4096
	ds_read_b128 v[186:189], v131
	ds_read_b128 v[190:193], v131 offset:4096
	ds_read_b128 v[230:233], v134
	ds_read_b128 v[234:237], v134 offset:4096
	ds_read_b128 v[238:241], v0
	ds_read_b128 v[242:245], v0 offset:4096
	s_and_b32 s0, s6, 0x18000
	s_add_i32 s11, s0, 0
	v_add3_u32 v0, s11, v216, v215
	ds_read_b128 v[174:177], v0 offset:16384
	ds_read_b128 v[170:173], v0 offset:20480
	ds_read_b128 v[166:169], v0 offset:24576
	ds_read_b128 v[162:165], v0 offset:28672
	v_add_f32_e32 v0, 0, v98
	v_add_f32_e32 v0, v99, v0
	v_add_f32_e32 v0, v100, v0
	v_add_f32_e32 v0, v101, v0
	v_cvt_pk_bf16_f32 v130, v98, v99
	v_cvt_pk_bf16_f32 v131, v100, v101
	s_nop 0
	v_add_f32_e32 v0, v102, v0
	v_add_f32_e32 v0, v103, v0
	v_add_f32_e32 v0, v104, v0
	v_add_f32_e32 v0, v105, v0
	v_cvt_pk_bf16_f32 v132, v102, v103
	v_cvt_pk_bf16_f32 v133, v104, v105
	s_nop 0
	v_add_f32_e32 v0, v106, v0
	v_add_f32_e32 v0, v107, v0
	v_add_f32_e32 v0, v108, v0
	v_add_f32_e32 v0, v109, v0
	v_cvt_pk_bf16_f32 v134, v106, v107
	v_cvt_pk_bf16_f32 v135, v108, v109
	s_nop 0
	v_add_f32_e32 v0, v110, v0
	v_add_f32_e32 v0, v111, v0
	v_add_f32_e32 v0, v112, v0
	v_add_f32_e32 v0, v113, v0
	v_cvt_pk_bf16_f32 v136, v110, v111
	v_cvt_pk_bf16_f32 v137, v112, v113
	s_nop 0
	v_add_f32_e32 v0, v82, v0
	v_add_f32_e32 v0, v83, v0
	v_add_f32_e32 v0, v84, v0
	v_add_f32_e32 v0, v85, v0
	v_cvt_pk_bf16_f32 v138, v82, v83
	v_cvt_pk_bf16_f32 v139, v84, v85
	s_nop 0
	v_add_f32_e32 v0, v86, v0
	v_add_f32_e32 v0, v87, v0
	v_add_f32_e32 v0, v88, v0
	v_add_f32_e32 v0, v89, v0
	v_cvt_pk_bf16_f32 v140, v86, v87
	v_cvt_pk_bf16_f32 v141, v88, v89
	s_nop 0
	v_add_f32_e32 v0, v90, v0
	v_add_f32_e32 v0, v91, v0
	v_add_f32_e32 v0, v92, v0
	v_add_f32_e32 v0, v93, v0
	v_cvt_pk_bf16_f32 v142, v90, v91
	v_cvt_pk_bf16_f32 v143, v92, v93
	s_nop 0
	v_add_f32_e32 v0, v94, v0
	v_add_f32_e32 v0, v95, v0
	v_add_f32_e32 v0, v96, v0
	v_add_f32_e32 v154, v97, v0
	v_cvt_pk_bf16_f32 v144, v94, v95
	v_cvt_pk_bf16_f32 v145, v96, v97
	s_nop 0
	s_waitcnt lgkmcnt(0)
	v_mfma_f32_32x32x16_bf16 v[98:113], v[178:181], v[114:117], v[66:81]
	v_add_u32_e32 v0, s11, v220
	s_add_i32 s0, s28, 64
	s_cmpk_gt_i32 s0, 0x7f
	v_add_u32_e32 v229, s28, v226
	v_mfma_f32_32x32x16_bf16 v[82:97], v[182:185], v[114:117], v[66:81]
	v_mfma_f32_32x32x16_bf16 v[98:113], v[186:189], v[118:121], v[98:113]
	v_mfma_f32_32x32x16_bf16 v[82:97], v[190:193], v[118:121], v[82:97]
	ds_read_b128 v[190:193], v0
	ds_read_b128 v[186:189], v0 offset:4096
	ds_read_b128 v[182:185], v0 offset:8192
	ds_read_b128 v[178:181], v0 offset:12288
	v_mfma_f32_32x32x16_bf16 v[98:113], v[230:233], v[122:125], v[98:113]
	v_mfma_f32_32x32x16_bf16 v[82:97], v[234:237], v[122:125], v[82:97]
	v_mfma_f32_32x32x16_bf16 v[98:113], v[238:241], v[126:129], v[98:113]
	v_mfma_f32_32x32x16_bf16 v[82:97], v[242:245], v[126:129], v[82:97]
	s_cbranch_scc1 .LBB0_265
	v_add_u32_e32 v0, 0x7f, v229
	v_add_u32_e32 v147, 0x7e, v229
	v_add_u32_e32 v151, 0x7d, v229
	v_add_u32_e32 v158, 0x7c, v229
	v_max_i32_e32 v146, -1, v0
	v_max_i32_e32 v0, 31, v0
	v_max_i32_e32 v150, -1, v147
	v_max_i32_e32 v147, 31, v147
	v_max_i32_e32 v155, -1, v151
	v_max_i32_e32 v151, 31, v151
	v_max_i32_e32 v159, -1, v158
	v_add_u32_e32 v146, 1, v146
	v_subrev_u32_e32 v0, 31, v0
	v_add_u32_e32 v150, 1, v150
	v_subrev_u32_e32 v147, 31, v147
	v_subrev_u32_e32 v151, 31, v151
	v_add_u32_e32 v159, 1, v159
	v_max_i32_e32 v158, 31, v158
	v_min_u32_e32 v146, 0x80, v146
	v_min_u32_e32 v0, 0x80, v0
	v_min_u32_e32 v150, 0x80, v150
	v_min_u32_e32 v147, 0x80, v147
	v_add_u32_e32 v155, 1, v155
	v_min_u32_e32 v151, 0x80, v151
	v_min_u32_e32 v159, 0x80, v159
	v_subrev_u32_e32 v158, 31, v158
	v_lshl_add_u32 v146, v146, 2, s100
	v_lshl_add_u32 v0, v0, 2, s100
	v_lshl_add_u32 v150, v150, 2, s100
	v_lshl_add_u32 v147, v147, 2, s100
	v_min_u32_e32 v155, 0x80, v155
	v_lshl_add_u32 v151, v151, 2, s100
	v_lshl_add_u32 v196, v159, 2, s100
	v_min_u32_e32 v158, 0x80, v158
	v_lshl_add_u32 v155, v155, 2, s100
	v_lshl_add_u32 v197, v158, 2, s100
	ds_read_b32 v158, v146
	ds_read_b32 v146, v0
	ds_read_b32 v159, v150
	ds_read_b32 v147, v147
	ds_read_b32 v230, v155
	ds_read_b32 v150, v151
	ds_read_b32 v231, v196
	ds_read_b32 v151, v197
	v_add_u32_e32 v0, 0x7b, v229
	v_add_u32_e32 v196, 0x7a, v229
	v_add_u32_e32 v232, 0x78, v229
	v_max_i32_e32 v155, -1, v0
	v_max_i32_e32 v0, 31, v0
	v_max_i32_e32 v197, -1, v196
	v_max_i32_e32 v196, 31, v196
	v_add_u32_e32 v212, 0x79, v229
	v_max_i32_e32 v233, -1, v232
	v_max_i32_e32 v232, 31, v232
	v_add_u32_e32 v155, 1, v155
	v_subrev_u32_e32 v0, 31, v0
	v_subrev_u32_e32 v196, 31, v196
	v_max_i32_e32 v213, -1, v212
	v_max_i32_e32 v212, 31, v212
	v_add_u32_e32 v233, 1, v233
	v_subrev_u32_e32 v232, 31, v232
	v_min_u32_e32 v155, 0x80, v155
	v_min_u32_e32 v0, 0x80, v0
	v_add_u32_e32 v197, 1, v197
	v_min_u32_e32 v196, 0x80, v196
	v_add_u32_e32 v213, 1, v213
	v_subrev_u32_e32 v212, 31, v212
	v_min_u32_e32 v233, 0x80, v233
	v_min_u32_e32 v232, 0x80, v232
	v_lshl_add_u32 v155, v155, 2, s100
	v_lshl_add_u32 v0, v0, 2, s100
	v_min_u32_e32 v197, 0x80, v197
	v_lshl_add_u32 v196, v196, 2, s100
	v_min_u32_e32 v213, 0x80, v213
	v_min_u32_e32 v212, 0x80, v212
	v_lshl_add_u32 v237, v233, 2, s100
	v_lshl_add_u32 v239, v232, 2, s100
	v_lshl_add_u32 v197, v197, 2, s100
	v_lshl_add_u32 v213, v213, 2, s100
	v_lshl_add_u32 v212, v212, 2, s100
	ds_read_b32 v232, v155
	ds_read_b32 v234, v0
	ds_read_b32 v233, v197
	ds_read_b32 v235, v196
	ds_read_b32 v236, v213
	ds_read_b32 v238, v212
	ds_read_b32 v237, v237
	ds_read_b32 v239, v239
	v_add_u32_e32 v0, 0x6f, v229
	v_add_u32_e32 v196, 0x6e, v229
	v_add_u32_e32 v240, 0x6c, v229
	v_max_i32_e32 v155, -1, v0
	v_max_i32_e32 v197, -1, v196
	v_max_i32_e32 v196, 31, v196
	v_add_u32_e32 v212, 0x6d, v229
	v_max_i32_e32 v241, -1, v240
	v_max_i32_e32 v240, 31, v240
	v_add_u32_e32 v155, 1, v155
	v_max_i32_e32 v0, 31, v0
	v_subrev_u32_e32 v196, 31, v196
	v_max_i32_e32 v213, -1, v212
	v_max_i32_e32 v212, 31, v212
	v_add_u32_e32 v241, 1, v241
	v_subrev_u32_e32 v240, 31, v240
	v_min_u32_e32 v155, 0x80, v155
	v_subrev_u32_e32 v0, 31, v0
	v_add_u32_e32 v197, 1, v197
	v_min_u32_e32 v196, 0x80, v196
	v_add_u32_e32 v213, 1, v213
	v_subrev_u32_e32 v212, 31, v212
	v_min_u32_e32 v241, 0x80, v241
	v_min_u32_e32 v240, 0x80, v240
	v_lshl_add_u32 v155, v155, 2, s100
	v_min_u32_e32 v0, 0x80, v0
	v_min_u32_e32 v197, 0x80, v197
	v_lshl_add_u32 v196, v196, 2, s100
	v_min_u32_e32 v213, 0x80, v213
	v_min_u32_e32 v212, 0x80, v212
	v_lshl_add_u32 v245, v241, 2, s100
	v_lshl_add_u32 v247, v240, 2, s100
	v_lshl_add_u32 v0, v0, 2, s100
	v_lshl_add_u32 v197, v197, 2, s100
	v_lshl_add_u32 v213, v213, 2, s100
	v_lshl_add_u32 v212, v212, 2, s100
	ds_read_b32 v240, v155
	ds_read_b32 v242, v0
	ds_read_b32 v241, v197
	ds_read_b32 v243, v196
	ds_read_b32 v244, v213
	ds_read_b32 v246, v212
	ds_read_b32 v245, v245
	ds_read_b32 v247, v247
	v_add_u32_e32 v196, 0x6a, v229
	v_max_i32_e32 v197, -1, v196
	v_max_i32_e32 v196, 31, v196
	v_subrev_u32_e32 v196, 31, v196
	v_min_u32_e32 v196, 0x80, v196
	v_add_u32_e32 v0, 0x6b, v229
	v_lshl_add_u32 v251, v196, 2, s100
	v_add_u32_e32 v196, 0x69, v229
	v_add_u32_e32 v213, 0x68, v229
	v_max_i32_e32 v155, -1, v0
	v_max_i32_e32 v212, -1, v196
	v_max_i32_e32 v196, 31, v196
	v_max_i32_e32 v248, -1, v213
	v_add_u32_e32 v155, 1, v155
	v_max_i32_e32 v0, 31, v0
	v_add_u32_e32 v197, 1, v197
	v_add_u32_e32 v212, 1, v212
	v_subrev_u32_e32 v196, 31, v196
	v_add_u32_e32 v248, 1, v248
	v_max_i32_e32 v213, 31, v213
	v_min_u32_e32 v155, 0x80, v155
	v_subrev_u32_e32 v0, 31, v0
	v_min_u32_e32 v197, 0x80, v197
	v_min_u32_e32 v212, 0x80, v212
	v_min_u32_e32 v196, 0x80, v196
	v_min_u32_e32 v248, 0x80, v248
	v_subrev_u32_e32 v213, 31, v213
	v_lshl_add_u32 v155, v155, 2, s100
	v_min_u32_e32 v0, 0x80, v0
	v_lshl_add_u32 v197, v197, 2, s100
	v_lshl_add_u32 v212, v212, 2, s100
	v_lshl_add_u32 v196, v196, 2, s100
	v_lshl_add_u32 v249, v248, 2, s100
	v_min_u32_e32 v213, 0x80, v213
	v_lshl_add_u32 v0, v0, 2, s100
	v_lshl_add_u32 v209, v213, 2, s100
	ds_read_b32 v248, v155
	ds_read_b32 v250, v0
	ds_read_b32 v212, v212
	ds_read_b32 v213, v249
	ds_read_b32 v249, v197
	ds_read_b32 v197, v209
	ds_read_b32 v196, v196
	ds_read_b32 v251, v251
	s_waitcnt lgkmcnt(0)
	v_pk_add_f32 v[112:113], v[112:113], v[212:213]
	v_pk_add_f32 v[110:111], v[110:111], v[248:249]
	v_pk_add_f32 v[108:109], v[108:109], v[244:245]
	v_pk_add_f32 v[106:107], v[106:107], v[240:241]
	v_pk_add_f32 v[104:105], v[104:105], v[236:237]
	v_pk_add_f32 v[102:103], v[102:103], v[232:233]
	v_pk_add_f32 v[100:101], v[100:101], v[230:231]
	v_pk_add_f32 v[98:99], v[98:99], v[158:159]
	v_pk_add_f32 v[96:97], v[96:97], v[196:197]
	v_pk_add_f32 v[94:95], v[94:95], v[250:251]
	v_pk_add_f32 v[92:93], v[92:93], v[246:247]
	v_pk_add_f32 v[90:91], v[90:91], v[242:243]
	v_pk_add_f32 v[88:89], v[88:89], v[238:239]
	v_pk_add_f32 v[86:87], v[86:87], v[234:235]
	v_pk_add_f32 v[84:85], v[84:85], v[150:151]
	v_pk_add_f32 v[82:83], v[82:83], v[146:147]

.LBB0_276:
	s_cmp_lt_u32 s9, s22
	s_cselect_b32 s84, s9, s27
	s_lshl_b64 s[0:1], s[84:85], 18
	v_lshl_add_u64 v[130:131], v[204:205], 0, s[0:1]
	v_lshl_add_u64 v[134:135], v[206:207], 0, s[0:1]
	s_and_b32 s0, s29, 0x18000
	s_add_i32 s0, s19, s0
	s_mov_b32 m0, s0
	s_waitcnt vmcnt(4)
	s_barrier
	global_load_lds_dwordx4 v[130:131], off
	v_lshl_add_u64 v[130:131], v[130:131], 0, s[72:73]
	s_add_i32 m0, s0, 0x2000
	s_nop 0
	global_load_lds_dwordx4 v[130:131], off
	s_add_i32 m0, s0, 0x4000
	v_lshl_add_u64 v[130:131], v[134:135], 0, s[96:97]
	global_load_lds_dwordx4 v[134:135], off
	s_add_i32 m0, s0, 0x6000
	s_add_i32 s0, s29, 0xffff0000
	global_load_lds_dwordx4 v[130:131], off
	s_and_b32 s0, s0, 0x18000
	v_add_u32_e32 v0, s0, v219
	v_add_u32_e32 v130, v0, v218
	v_add_u32_e32 v131, v0, v223
	v_add_u32_e32 v134, v0, v224
	v_add_u32_e32 v0, v0, v225
	ds_read_b128 v[178:181], v130
	ds_read_b128 v[182:185], v130 offset:4096
	ds_read_b128 v[186:189], v131
	ds_read_b128 v[190:193], v131 offset:4096
	ds_read_b128 v[230:233], v134
	ds_read_b128 v[234:237], v134 offset:4096
	ds_read_b128 v[238:241], v0
	ds_read_b128 v[242:245], v0 offset:4096
	v_add3_u32 v0, s10, v216, v215
	ds_read_b128 v[174:177], v0 offset:16384
	ds_read_b128 v[170:173], v0 offset:20480
	ds_read_b128 v[166:169], v0 offset:24576
	ds_read_b128 v[162:165], v0 offset:28672
	v_add_f32_e32 v0, 0, v98
	v_add_f32_e32 v0, v99, v0
	v_add_f32_e32 v0, v100, v0
	v_add_f32_e32 v0, v101, v0
	v_cvt_pk_bf16_f32 v158, v98, v99
	v_cvt_pk_bf16_f32 v159, v100, v101
	s_nop 0
	v_add_f32_e32 v0, v102, v0
	v_add_f32_e32 v0, v103, v0
	v_add_f32_e32 v0, v104, v0
	v_add_f32_e32 v0, v105, v0
	v_cvt_pk_bf16_f32 v160, v102, v103
	v_cvt_pk_bf16_f32 v161, v104, v105
	s_nop 0
	v_add_f32_e32 v0, v106, v0
	v_add_f32_e32 v0, v107, v0
	v_add_f32_e32 v0, v108, v0
	v_add_f32_e32 v0, v109, v0
	v_cvt_pk_bf16_f32 v154, v106, v107
	v_cvt_pk_bf16_f32 v155, v108, v109
	s_nop 0
	v_add_f32_e32 v0, v110, v0
	v_add_f32_e32 v0, v111, v0
	v_add_f32_e32 v0, v112, v0
	v_add_f32_e32 v0, v113, v0
	v_cvt_pk_bf16_f32 v156, v110, v111
	v_cvt_pk_bf16_f32 v157, v112, v113
	s_nop 0
	v_add_f32_e32 v0, v82, v0
	v_add_f32_e32 v0, v83, v0
	v_add_f32_e32 v0, v84, v0
	v_add_f32_e32 v0, v85, v0
	v_cvt_pk_bf16_f32 v150, v82, v83
	v_cvt_pk_bf16_f32 v151, v84, v85
	s_nop 0
	v_add_f32_e32 v0, v86, v0
	v_add_f32_e32 v0, v87, v0
	v_add_f32_e32 v0, v88, v0
	v_add_f32_e32 v0, v89, v0
	v_cvt_pk_bf16_f32 v152, v86, v87
	v_cvt_pk_bf16_f32 v153, v88, v89
	s_nop 0
	v_add_f32_e32 v0, v90, v0
	v_add_f32_e32 v0, v91, v0
	v_add_f32_e32 v0, v92, v0
	v_add_f32_e32 v0, v93, v0
	v_cvt_pk_bf16_f32 v146, v90, v91
	v_cvt_pk_bf16_f32 v147, v92, v93
	s_nop 0
	v_add_f32_e32 v0, v94, v0
	v_add_f32_e32 v0, v95, v0
	v_add_f32_e32 v0, v96, v0
	v_add_f32_e32 v138, v97, v0
	v_cvt_pk_bf16_f32 v148, v94, v95
	v_cvt_pk_bf16_f32 v149, v96, v97
	s_nop 0
	s_waitcnt lgkmcnt(0)
	v_mfma_f32_32x32x16_bf16 v[98:113], v[178:181], v[114:117], v[66:81]
	v_add_u32_e32 v0, s10, v220
	s_cmpk_gt_i32 s28, 0x7f
	v_mfma_f32_32x32x16_bf16 v[82:97], v[182:185], v[114:117], v[66:81]
	v_mfma_f32_32x32x16_bf16 v[98:113], v[186:189], v[118:121], v[98:113]
	v_mfma_f32_32x32x16_bf16 v[82:97], v[190:193], v[118:121], v[82:97]
	ds_read_b128 v[190:193], v0
	ds_read_b128 v[186:189], v0 offset:4096
	ds_read_b128 v[182:185], v0 offset:8192
	ds_read_b128 v[178:181], v0 offset:12288
	v_mfma_f32_32x32x16_bf16 v[98:113], v[230:233], v[122:125], v[98:113]
	v_mfma_f32_32x32x16_bf16 v[82:97], v[234:237], v[122:125], v[82:97]
	v_mfma_f32_32x32x16_bf16 v[98:113], v[238:241], v[126:129], v[98:113]
	v_mfma_f32_32x32x16_bf16 v[82:97], v[242:245], v[126:129], v[82:97]
	s_cbranch_scc1 .LBB0_278
	v_add_u32_e32 v0, 63, v229
	v_add_u32_e32 v131, 62, v229
	v_add_u32_e32 v135, 61, v229
	v_add_u32_e32 v142, 60, v229
	v_max_i32_e32 v130, -1, v0
	v_max_i32_e32 v134, -1, v131
	v_max_i32_e32 v131, 31, v131
	v_max_i32_e32 v139, -1, v135
	v_max_i32_e32 v135, 31, v135
	v_max_i32_e32 v143, -1, v142
	v_max_i32_e32 v142, 31, v142
	v_add_u32_e32 v130, 1, v130
	v_max_i32_e32 v0, 31, v0
	v_add_u32_e32 v134, 1, v134
	v_subrev_u32_e32 v131, 31, v131
	v_subrev_u32_e32 v135, 31, v135
	v_add_u32_e32 v143, 1, v143
	v_subrev_u32_e32 v142, 31, v142
	v_min_u32_e32 v130, 0x80, v130
	v_subrev_u32_e32 v0, 31, v0
	v_min_u32_e32 v134, 0x80, v134
	v_min_u32_e32 v131, 0x80, v131
	v_add_u32_e32 v139, 1, v139
	v_min_u32_e32 v135, 0x80, v135
	v_min_u32_e32 v143, 0x80, v143
	v_min_u32_e32 v142, 0x80, v142
	v_lshl_add_u32 v130, v130, 2, s100
	v_min_u32_e32 v0, 0x80, v0
	v_lshl_add_u32 v134, v134, 2, s100
	v_lshl_add_u32 v131, v131, 2, s100
	v_min_u32_e32 v139, 0x80, v139
	v_lshl_add_u32 v135, v135, 2, s100
	v_lshl_add_u32 v197, v143, 2, s100
	v_lshl_add_u32 v209, v142, 2, s100
	v_lshl_add_u32 v0, v0, 2, s100
	v_lshl_add_u32 v139, v139, 2, s100
	ds_read_b32 v142, v130
	ds_read_b32 v130, v0
	ds_read_b32 v143, v134
	ds_read_b32 v131, v131
	ds_read_b32 v196, v139
	ds_read_b32 v134, v135
	ds_read_b32 v197, v197
	ds_read_b32 v135, v209
	v_add_u32_e32 v209, 58, v229
	v_max_i32_e32 v212, -1, v209
	v_add_u32_e32 v212, 1, v212
	v_min_u32_e32 v212, 0x80, v212
	v_lshl_add_u32 v213, v212, 2, s100
	v_add_u32_e32 v212, 57, v229
	v_max_i32_e32 v230, -1, v212
	v_max_i32_e32 v212, 31, v212
	v_subrev_u32_e32 v212, 31, v212
	v_add_u32_e32 v230, 1, v230
	v_min_u32_e32 v212, 0x80, v212
	v_add_u32_e32 v0, 59, v229
	v_min_u32_e32 v230, 0x80, v230
	v_lshl_add_u32 v233, v212, 2, s100
	v_add_u32_e32 v212, 56, v229
	v_max_i32_e32 v139, -1, v0
	v_max_i32_e32 v209, 31, v209
	v_lshl_add_u32 v232, v230, 2, s100
	v_max_i32_e32 v230, -1, v212
	v_add_u32_e32 v139, 1, v139
	v_max_i32_e32 v0, 31, v0
	v_subrev_u32_e32 v209, 31, v209
	v_add_u32_e32 v230, 1, v230
	v_max_i32_e32 v212, 31, v212
	v_min_u32_e32 v139, 0x80, v139
	v_subrev_u32_e32 v0, 31, v0
	v_min_u32_e32 v209, 0x80, v209
	v_min_u32_e32 v230, 0x80, v230
	v_subrev_u32_e32 v212, 31, v212
	v_lshl_add_u32 v139, v139, 2, s100
	v_min_u32_e32 v0, 0x80, v0
	v_lshl_add_u32 v209, v209, 2, s100
	v_lshl_add_u32 v235, v230, 2, s100
	v_min_u32_e32 v212, 0x80, v212
	v_lshl_add_u32 v0, v0, 2, s100
	v_lshl_add_u32 v236, v212, 2, s100
	ds_read_b32 v212, v139
	ds_read_b32 v230, v0
	ds_read_b32 v213, v213
	ds_read_b32 v231, v209
	ds_read_b32 v232, v232
	ds_read_b32 v234, v233
	ds_read_b32 v233, v235
	ds_read_b32 v235, v236
	v_add_u32_e32 v209, 46, v229
	v_max_i32_e32 v236, -1, v209
	v_add_u32_e32 v236, 1, v236
	v_min_u32_e32 v236, 0x80, v236
	v_lshl_add_u32 v237, v236, 2, s100
	v_add_u32_e32 v236, 45, v229
	v_max_i32_e32 v238, -1, v236
	v_max_i32_e32 v236, 31, v236
	v_subrev_u32_e32 v236, 31, v236
	v_add_u32_e32 v238, 1, v238
	v_min_u32_e32 v236, 0x80, v236
	v_add_u32_e32 v0, 47, v229
	v_min_u32_e32 v238, 0x80, v238
	v_lshl_add_u32 v241, v236, 2, s100
	v_add_u32_e32 v236, 44, v229
	v_max_i32_e32 v139, -1, v0
	v_max_i32_e32 v209, 31, v209
	v_lshl_add_u32 v240, v238, 2, s100
	v_max_i32_e32 v238, -1, v236
	v_add_u32_e32 v139, 1, v139
	v_max_i32_e32 v0, 31, v0
	v_subrev_u32_e32 v209, 31, v209
	v_add_u32_e32 v238, 1, v238
	v_max_i32_e32 v236, 31, v236
	v_min_u32_e32 v139, 0x80, v139
	v_subrev_u32_e32 v0, 31, v0
	v_min_u32_e32 v209, 0x80, v209
	v_min_u32_e32 v238, 0x80, v238
	v_subrev_u32_e32 v236, 31, v236
	v_lshl_add_u32 v139, v139, 2, s100
	v_min_u32_e32 v0, 0x80, v0
	v_lshl_add_u32 v209, v209, 2, s100
	v_lshl_add_u32 v243, v238, 2, s100
	v_min_u32_e32 v236, 0x80, v236
	v_lshl_add_u32 v0, v0, 2, s100
	v_lshl_add_u32 v244, v236, 2, s100
	ds_read_b32 v236, v139
	ds_read_b32 v238, v0
	ds_read_b32 v237, v237
	ds_read_b32 v239, v209
	ds_read_b32 v240, v240
	ds_read_b32 v242, v241
	ds_read_b32 v241, v243
	ds_read_b32 v243, v244
	v_add_u32_e32 v209, 42, v229
	v_max_i32_e32 v244, -1, v209
	v_add_u32_e32 v244, 1, v244
	v_min_u32_e32 v244, 0x80, v244
	v_lshl_add_u32 v245, v244, 2, s100
	v_add_u32_e32 v244, 41, v229
	v_max_i32_e32 v246, -1, v244
	v_max_i32_e32 v244, 31, v244
	v_subrev_u32_e32 v244, 31, v244
	v_add_u32_e32 v0, 43, v229
	v_min_u32_e32 v244, 0x80, v244
	v_add_u32_e32 v229, 40, v229
	v_max_i32_e32 v139, -1, v0
	v_lshl_add_u32 v250, v244, 2, s100
	v_max_i32_e32 v244, -1, v229
	v_add_u32_e32 v139, 1, v139
	v_max_i32_e32 v0, 31, v0
	v_max_i32_e32 v209, 31, v209
	v_add_u32_e32 v246, 1, v246
	v_add_u32_e32 v244, 1, v244
	v_max_i32_e32 v229, 31, v229
	v_min_u32_e32 v139, 0x80, v139
	v_subrev_u32_e32 v0, 31, v0
	v_subrev_u32_e32 v209, 31, v209
	v_min_u32_e32 v246, 0x80, v246
	v_min_u32_e32 v244, 0x80, v244
	v_subrev_u32_e32 v229, 31, v229
	v_lshl_add_u32 v139, v139, 2, s100
	v_min_u32_e32 v0, 0x80, v0
	v_min_u32_e32 v209, 0x80, v209
	v_lshl_add_u32 v247, v246, 2, s100
	v_lshl_add_u32 v249, v244, 2, s100
	v_min_u32_e32 v229, 0x80, v229
	v_lshl_add_u32 v0, v0, 2, s100
	v_lshl_add_u32 v209, v209, 2, s100
	v_lshl_add_u32 v229, v229, 2, s100
	ds_read_b32 v244, v139
	ds_read_b32 v246, v0
	ds_read_b32 v248, v247
	ds_read_b32 v249, v249
	ds_read_b32 v245, v245
	ds_read_b32 v251, v229
	ds_read_b32 v250, v250
	ds_read_b32 v247, v209
	s_waitcnt lgkmcnt(0)
	v_pk_add_f32 v[112:113], v[112:113], v[248:249]
	v_pk_add_f32 v[110:111], v[110:111], v[244:245]
	v_pk_add_f32 v[108:109], v[108:109], v[240:241]
	v_pk_add_f32 v[106:107], v[106:107], v[236:237]
	v_pk_add_f32 v[104:105], v[104:105], v[232:233]
	v_pk_add_f32 v[102:103], v[102:103], v[212:213]
	v_pk_add_f32 v[100:101], v[100:101], v[196:197]
	v_pk_add_f32 v[98:99], v[98:99], v[142:143]
	v_pk_add_f32 v[96:97], v[96:97], v[250:251]
	v_pk_add_f32 v[94:95], v[94:95], v[246:247]
	v_pk_add_f32 v[92:93], v[92:93], v[242:243]
	v_pk_add_f32 v[90:91], v[90:91], v[238:239]
	v_pk_add_f32 v[88:89], v[88:89], v[234:235]
	v_pk_add_f32 v[86:87], v[86:87], v[230:231]
	v_pk_add_f32 v[84:85], v[84:85], v[134:135]
	v_pk_add_f32 v[82:83], v[82:83], v[130:131]

.LBB0_495:
	s_or_b64 exec, exec, s[40:41]
	v_mov_b32_e32 v0, v208
	s_movk_i32 s6, 0x100
	s_waitcnt lgkmcnt(0)
	s_barrier
	s_movk_i32 s8, 0xc800
	v_cmp_gt_i32_e64 s[40:41], s6, v0
	v_lshl_add_u32 v2, v0, 2, s90
	v_lshlrev_b32_e32 v42, 4, v0
	v_add_u32_e32 v43, 0x1000, v42
	v_add_u32_e32 v44, 0x2000, v42
	v_add_u32_e32 v45, 0x3000, v42
	v_add_u32_e32 v46, 0x4000, v42
	v_add_u32_e32 v47, 0x5000, v42
	v_add_u32_e32 v48, 0x6000, v42
	v_add_u32_e32 v49, 0x7000, v42
	v_and_b32_e32 v50, 1, v0
	v_and_b32_e32 v51, 2, v0
	v_and_b32_e32 v52, 4, v0
	v_and_b32_e32 v53, 7, v0
	v_lshrrev_b32_e32 v54, 3, v0
	v_lshl_add_u32 v53, v53, 5, v54
	v_lshl_add_u32 v53, v53, 2, s90
	s_mov_b64 s[44:45], s[2:3]
	s_branch .LBB0_498

.LBB0_498:
	v_cmp_gt_i64_e32 vcc, s[44:45], v[198:199]
	s_mov_b64 s[46:47], -1
	s_cbranch_vccnz .LBB0_497
	s_and_saveexec_b64 s[46:47], s[40:41]
	s_cbranch_execz .LBB0_496
	s_ashr_i32 s6, s44, 31
	s_lshr_b32 s6, s6, 29
	s_add_i32 s6, s44, s6
	s_ashr_i32 s7, s6, 3
	s_and_b32 s6, s6, -8
	s_sub_i32 s6, s44, s6
	s_cmp_lt_i32 s6, 0
	s_movk_i32 s9, 0x161
	s_cselect_b32 s9, s9, 0x160
	s_mul_i32 s6, s6, s9
	s_add_i32 s6, s6, s7
	s_mul_hi_i32 s7, s6, 0x2e8ba2e9
	s_lshr_b32 s9, s7, 31
	s_ashr_i32 s7, s7, 6
	s_add_i32 s7, s7, s9
	s_mul_i32 s9, s7, 0x160
	s_lshl_b32 s7, s7, 3
	s_sub_i32 s6, s6, s9
	s_sub_i32 s9, 64, s7
	s_min_i32 s9, s9, 8
	s_abs_i32 s9, s9
	v_cvt_f32_u32_e32 v3, s9
	s_sub_i32 s11, 0, s9
	s_ashr_i32 s10, s6, 31
	s_abs_i32 s6, s6
	v_rcp_iflag_f32_e32 v3, v3
	s_nop 0
	v_mul_f32_e32 v3, 0x4f7ffffe, v3
	v_cvt_u32_f32_e32 v3, v3
	s_nop 0
	v_readfirstlane_b32 s12, v3
	s_mul_i32 s11, s11, s12
	s_mul_hi_u32 s11, s12, s11
	s_add_i32 s12, s12, s11
	s_mul_hi_u32 s11, s6, s12
	s_mul_i32 s11, s11, s9
	s_sub_i32 s6, s6, s11
	s_sub_i32 s11, s6, s9
	s_cmp_ge_u32 s6, s9
	s_cselect_b32 s6, s11, s6
	s_sub_i32 s11, s6, s9
	s_cmp_ge_u32 s6, s9
	s_cselect_b32 s6, s11, s6
	s_xor_b32 s6, s6, s10
	s_sub_i32 s6, s6, s10
	s_add_i32 s6, s6, s7
	s_lshl_b32 s7, s6, 15
	s_add_u32 s10, s0, s7
	s_addc_u32 s11, s1, 0
	s_nop 1
	global_load_dwordx4 v[4:7], v42, s[10:11]
	global_load_dwordx4 v[8:11], v43, s[10:11]
	global_load_dwordx4 v[12:15], v44, s[10:11]
	global_load_dwordx4 v[16:19], v45, s[10:11]
	global_load_dwordx4 v[26:29], v46, s[10:11]
	global_load_dwordx4 v[30:33], v47, s[10:11]
	global_load_dwordx4 v[34:37], v48, s[10:11]
	global_load_dwordx4 v[38:41], v49, s[10:11]
	s_waitcnt vmcnt(0)
	v_add_f32_e32 v4, v4, v5
	v_add_f32_e32 v8, v8, v9
	v_add_f32_e32 v12, v12, v13
	v_add_f32_e32 v16, v16, v17
	v_add_f32_e32 v26, v26, v27
	v_add_f32_e32 v30, v30, v31
	v_add_f32_e32 v34, v34, v35
	v_add_f32_e32 v38, v38, v39
	v_add_f32_e32 v6, v6, v7
	v_add_f32_e32 v10, v10, v11
	v_add_f32_e32 v14, v14, v15
	v_add_f32_e32 v18, v18, v19
	v_add_f32_e32 v28, v28, v29
	v_add_f32_e32 v32, v32, v33
	v_add_f32_e32 v36, v36, v37
	v_add_f32_e32 v40, v40, v41
	v_add_f32_e32 v4, v4, v6
	v_add_f32_e32 v8, v8, v10
	v_add_f32_e32 v12, v12, v14
	v_add_f32_e32 v16, v16, v18
	v_add_f32_e32 v26, v26, v28
	v_add_f32_e32 v30, v30, v32
	v_add_f32_e32 v34, v34, v36
	v_add_f32_e32 v38, v38, v40
	v_add_f32_dpp v4, v4, v4 quad_perm:[1,0,3,2] row_mask:0xf bank_mask:0xf
	v_add_f32_dpp v8, v8, v8 quad_perm:[1,0,3,2] row_mask:0xf bank_mask:0xf
	v_add_f32_dpp v12, v12, v12 quad_perm:[1,0,3,2] row_mask:0xf bank_mask:0xf
	v_add_f32_dpp v16, v16, v16 quad_perm:[1,0,3,2] row_mask:0xf bank_mask:0xf
	v_add_f32_dpp v26, v26, v26 quad_perm:[1,0,3,2] row_mask:0xf bank_mask:0xf
	v_add_f32_dpp v30, v30, v30 quad_perm:[1,0,3,2] row_mask:0xf bank_mask:0xf
	v_add_f32_dpp v34, v34, v34 quad_perm:[1,0,3,2] row_mask:0xf bank_mask:0xf
	v_add_f32_dpp v38, v38, v38 quad_perm:[1,0,3,2] row_mask:0xf bank_mask:0xf
	v_add_f32_dpp v4, v4, v4 quad_perm:[2,3,0,1] row_mask:0xf bank_mask:0xf
	v_add_f32_dpp v8, v8, v8 quad_perm:[2,3,0,1] row_mask:0xf bank_mask:0xf
	v_add_f32_dpp v12, v12, v12 quad_perm:[2,3,0,1] row_mask:0xf bank_mask:0xf
	v_add_f32_dpp v16, v16, v16 quad_perm:[2,3,0,1] row_mask:0xf bank_mask:0xf
	v_add_f32_dpp v26, v26, v26 quad_perm:[2,3,0,1] row_mask:0xf bank_mask:0xf
	v_add_f32_dpp v30, v30, v30 quad_perm:[2,3,0,1] row_mask:0xf bank_mask:0xf
	v_add_f32_dpp v34, v34, v34 quad_perm:[2,3,0,1] row_mask:0xf bank_mask:0xf
	v_add_f32_dpp v38, v38, v38 quad_perm:[2,3,0,1] row_mask:0xf bank_mask:0xf
	v_add_f32_dpp v4, v4, v4 row_half_mirror row_mask:0xf bank_mask:0xf
	v_add_f32_dpp v8, v8, v8 row_half_mirror row_mask:0xf bank_mask:0xf
	v_add_f32_dpp v12, v12, v12 row_half_mirror row_mask:0xf bank_mask:0xf
	v_add_f32_dpp v16, v16, v16 row_half_mirror row_mask:0xf bank_mask:0xf
	v_add_f32_dpp v26, v26, v26 row_half_mirror row_mask:0xf bank_mask:0xf
	v_add_f32_dpp v30, v30, v30 row_half_mirror row_mask:0xf bank_mask:0xf
	v_add_f32_dpp v34, v34, v34 row_half_mirror row_mask:0xf bank_mask:0xf
	v_add_f32_dpp v38, v38, v38 row_half_mirror row_mask:0xf bank_mask:0xf
	v_cmp_ne_u32_e32 vcc, 0, v50
	s_nop 1
	v_cndmask_b32_e32 v4, v4, v8, vcc
	v_cndmask_b32_e32 v12, v12, v16, vcc
	v_cndmask_b32_e32 v26, v26, v30, vcc
	v_cndmask_b32_e32 v34, v34, v38, vcc
	v_cmp_ne_u32_e32 vcc, 0, v51
	s_nop 1
	v_cndmask_b32_e32 v4, v4, v12, vcc
	v_cndmask_b32_e32 v26, v26, v34, vcc
	v_cmp_ne_u32_e32 vcc, 0, v52
	s_nop 1
	v_cndmask_b32_e32 v3, v4, v26, vcc
	v_mov_b32_e32 v4, 0x3727c5ac
	v_fmamk_f32 v3, v3, 0x3a000000, v4
	v_rsq_f32_e32 v3, v3
	v_add_u32_e32 v4, s8, v53
	ds_write_b32 v4, v3 offset:14336
	s_branch .LBB0_496
